# RMSNorm loop of phase 1: w/sc/sh loads of column groups 1-3 hoisted to the row top into fresh quads, consumers renamed, vmcnt counts re-derived (on top of v18)
# speedup vs baseline: 1.0181x; 1.0181x over previous
.LBB0_58:
	s_or_b64 exec, exec, s[4:5]
	v_lshl_add_u64 v[0:1], v[0:1], 0, v[30:31]
	global_load_dwordx4 v[74:77], v[0:1], off
	global_load_dwordx4 v[24:27], v[0:1], off offset:1024
	global_load_dwordx4 v[20:23], v[0:1], off offset:2048
	global_load_dwordx4 v[16:19], v[0:1], off offset:3072
	v_add_co_u32_e64 v62, s[4:5], s3, v0
	v_lshrrev_b32_e32 v47, 10, v60
	s_nop 0
	v_addc_co_u32_e64 v63, s[4:5], 0, v1, s[4:5]
	global_load_dwordx4 v[12:15], v[62:63], off
	global_load_dwordx4 v[8:11], v[62:63], off offset:1024
	global_load_dwordx4 v[4:7], v[62:63], off offset:2048
	global_load_dwordx4 v[0:3], v[62:63], off offset:3072
	v_add_u32_e32 v47, 1, v47
	v_mov_b64_e32 v[60:61], s[20:21]
	v_cndmask_b32_e64 v47, v47, 0, vcc
	v_mad_u64_u32 v[60:61], s[0:1], v47, s23, v[60:61]
	v_lshl_add_u64 v[62:63], v[60:61], 0, s[18:19]
	global_load_dwordx4 v[78:81], v[32:33], off
	v_lshl_add_u64 v[92:93], v[62:63], 0, v[30:31]
	v_lshl_add_u64 v[90:91], v[60:61], 0, v[30:31]
	global_load_dwordx4 v[82:85], v[92:93], off
	global_load_dwordx4 v[86:89], v[90:91], off
	global_load_dwordx4 v[120:123], v[32:33], off offset:1024
	global_load_dwordx4 v[124:127], v[92:93], off offset:1024
	global_load_dwordx4 v[128:131], v[90:91], off offset:1024
	global_load_dwordx4 v[132:135], v[32:33], off offset:2048
	global_load_dwordx4 v[136:139], v[92:93], off offset:2048
	global_load_dwordx4 v[140:143], v[90:91], off offset:2048
	global_load_dwordx4 v[144:147], v[32:33], off offset:3072
	global_load_dwordx4 v[148:151], v[92:93], off offset:3072
	global_load_dwordx4 v[152:155], v[90:91], off offset:3072
	v_lshlrev_b64 v[64:65], 12, v[64:65]
	v_lshl_add_u64 v[64:65], v[42:43], 0, v[64:65]
	v_mov_b32_e32 v55, v31
	v_mov_b32_e32 v57, v31
	v_mov_b32_e32 v59, v31
	v_lshl_add_u64 v[28:29], v[28:29], 0, s[12:13]
	v_lshl_add_u64 v[44:45], v[44:45], 0, s[14:15]
	s_waitcnt vmcnt(19)
	v_mul_f32_e32 v47, v75, v75
	s_waitcnt vmcnt(18)
	v_mul_f32_e32 v49, v25, v25
	s_waitcnt vmcnt(17)
	v_mul_f32_e32 v51, v21, v21
	v_fmac_f32_e32 v47, v74, v74
	v_fmac_f32_e32 v49, v24, v24
	s_waitcnt vmcnt(16)
	v_mul_f32_e32 v53, v17, v17
	v_fmac_f32_e32 v51, v20, v20
	s_waitcnt vmcnt(15)
	v_mov_b32_e32 v94, v13
	s_waitcnt vmcnt(14)
	v_mov_b32_e32 v95, v9
	v_fmac_f32_e32 v47, v76, v76
	v_fmac_f32_e32 v49, v26, v26
	v_fmac_f32_e32 v53, v16, v16
	v_mov_b32_e32 v92, v12
	v_mov_b32_e32 v93, v8
	v_fmac_f32_e32 v51, v22, v22
	v_pk_mul_f32 v[94:95], v[94:95], v[94:95]
	v_fmac_f32_e32 v47, v77, v77
	v_fmac_f32_e32 v49, v27, v27
	v_mov_b32_e32 v96, v14
	v_mov_b32_e32 v97, v10
	s_waitcnt vmcnt(13)
	v_mov_b32_e32 v102, v5
	s_waitcnt vmcnt(12)
	v_mov_b32_e32 v103, v1
	v_fmac_f32_e32 v53, v18, v18
	v_fmac_f32_e32 v51, v23, v23
	v_pk_fma_f32 v[92:93], v[92:93], v[92:93], v[94:95]
	v_add_f32_e32 v47, v47, v49
	v_mov_b32_e32 v98, v15
	v_mov_b32_e32 v99, v11
	v_mov_b32_e32 v100, v4
	v_mov_b32_e32 v101, v0
	v_pk_mul_f32 v[102:103], v[102:103], v[102:103]
	v_fmac_f32_e32 v53, v19, v19
	v_pk_fma_f32 v[92:93], v[96:97], v[96:97], v[92:93]
	v_add_f32_e32 v47, v47, v51
	v_mov_b32_e32 v104, v6
	v_mov_b32_e32 v105, v2
	v_pk_fma_f32 v[94:95], v[100:101], v[100:101], v[102:103]
	v_pk_fma_f32 v[92:93], v[98:99], v[98:99], v[92:93]
	v_add_f32_e32 v47, v47, v53
	v_mov_b32_e32 v106, v7
	v_mov_b32_e32 v107, v3
	v_pk_fma_f32 v[94:95], v[104:105], v[104:105], v[94:95]
	v_add_f32_e32 v47, v47, v92
	v_pk_fma_f32 v[94:95], v[106:107], v[106:107], v[94:95]
	v_add_f32_e32 v47, v47, v93
	v_add_f32_e32 v47, v47, v94
	v_add_f32_e32 v47, v47, v95
	ds_bpermute_b32 v49, v67, v47
	s_waitcnt vmcnt(10)
	v_pk_add_f32 v[82:83], v[82:83], 1.0 op_sel_hi:[1,0]
	v_pk_add_f32 v[84:85], v[84:85], 1.0 op_sel_hi:[1,0]
	v_mov_b32_e32 v53, v31
	s_waitcnt lgkmcnt(0)
	v_add_f32_e32 v47, v47, v49
	ds_bpermute_b32 v49, v68, v47
	s_waitcnt lgkmcnt(0)
	v_add_f32_e32 v47, v47, v49
	ds_bpermute_b32 v49, v69, v47
	s_waitcnt lgkmcnt(0)
	v_add_f32_e32 v47, v47, v49
	ds_bpermute_b32 v49, v70, v47
	s_waitcnt lgkmcnt(0)
	v_add_f32_e32 v47, v47, v49
	ds_bpermute_b32 v49, v71, v47
	s_waitcnt lgkmcnt(0)
	v_add_f32_e32 v49, v47, v49
	ds_bpermute_b32 v51, v72, v49
	v_mov_b32_e32 v47, v31
	s_waitcnt lgkmcnt(0)
	v_add_f32_e32 v49, v49, v51
	v_fmamk_f32 v49, v49, 0x3a000000, v73
	v_mul_f32_e32 v51, 0x4b800000, v49
	v_cmp_gt_f32_e32 vcc, s24, v49
	s_nop 1
	v_cndmask_b32_e32 v49, v49, v51, vcc
	v_rsq_f32_e32 v49, v49
	s_nop 0
	v_mul_f32_e32 v51, 0x45800000, v49
	v_cndmask_b32_e32 v66, v49, v51, vcc
	v_pk_mul_f32 v[74:75], v[74:75], v[66:67] op_sel_hi:[1,0]
	v_pk_mul_f32 v[76:77], v[76:77], v[66:67] op_sel_hi:[1,0]
	v_pk_mul_f32 v[74:75], v[78:79], v[74:75]
	v_pk_mul_f32 v[76:77], v[80:81], v[76:77]
	s_waitcnt vmcnt(9)
	v_pk_fma_f32 v[74:75], v[82:83], v[74:75], v[86:87]
	v_pk_fma_f32 v[76:77], v[84:85], v[76:77], v[88:89]
	v_cvt_pk_bf16_f32 v74, v74, v75
	v_lshl_add_u64 v[86:87], v[62:63], 0, v[46:47]
	v_cvt_pk_bf16_f32 v75, v76, v77
	global_store_dwordx2 v[64:65], v[74:75], off
	s_nop 0
	v_pk_mul_f32 v[26:27], v[26:27], v[66:67] op_sel_hi:[1,0]
	v_pk_mul_f32 v[24:25], v[24:25], v[66:67] op_sel_hi:[1,0]
	v_mov_b32_e32 v49, v31
	v_pk_mul_f32 v[22:23], v[22:23], v[66:67] op_sel_hi:[1,0]
	v_pk_mul_f32 v[20:21], v[20:21], v[66:67] op_sel_hi:[1,0]
	v_mov_b32_e32 v51, v31
	v_pk_mul_f32 v[18:19], v[18:19], v[66:67] op_sel_hi:[1,0]
	v_pk_mul_f32 v[16:17], v[16:17], v[66:67] op_sel_hi:[1,0]
	v_pk_mul_f32 v[14:15], v[14:15], v[66:67] op_sel_hi:[1,0]
	v_pk_mul_f32 v[12:13], v[12:13], v[66:67] op_sel_hi:[1,0]
	v_pk_mul_f32 v[10:11], v[10:11], v[66:67] op_sel_hi:[1,0]
	v_pk_mul_f32 v[8:9], v[8:9], v[66:67] op_sel_hi:[1,0]
	v_pk_mul_f32 v[6:7], v[6:7], v[66:67] op_sel_hi:[1,0]
	v_pk_mul_f32 v[4:5], v[4:5], v[66:67] op_sel_hi:[1,0]
	v_pk_mul_f32 v[2:3], v[2:3], v[66:67] op_sel_hi:[1,0]
	v_pk_mul_f32 v[0:1], v[0:1], v[66:67] op_sel_hi:[1,0]
	v_cmp_lt_i32_e32 vcc, s25, v28
	s_or_b64 s[16:17], vcc, s[16:17]
	s_waitcnt vmcnt(9)
	v_pk_mul_f32 v[24:25], v[120:121], v[24:25]
	v_pk_mul_f32 v[26:27], v[122:123], v[26:27]
	s_waitcnt vmcnt(8)
	v_pk_add_f32 v[76:77], v[124:125], 1.0 op_sel_hi:[1,0]
	v_pk_add_f32 v[74:75], v[126:127], 1.0 op_sel_hi:[1,0]
	s_waitcnt vmcnt(7)
	v_pk_fma_f32 v[24:25], v[76:77], v[24:25], v[128:129]
	v_pk_fma_f32 v[26:27], v[74:75], v[26:27], v[130:131]
	v_cvt_pk_bf16_f32 v24, v24, v25
	v_lshl_add_u64 v[82:83], v[62:63], 0, v[48:49]
	v_cvt_pk_bf16_f32 v25, v26, v27
	global_store_dwordx2 v[64:65], v[24:25], off offset:512
	s_nop 0
	s_waitcnt vmcnt(7)
	v_pk_mul_f32 v[20:21], v[132:133], v[20:21]
	v_pk_mul_f32 v[22:23], v[134:135], v[22:23]
	s_waitcnt vmcnt(6)
	v_pk_add_f32 v[26:27], v[136:137], 1.0 op_sel_hi:[1,0]
	v_pk_add_f32 v[24:25], v[138:139], 1.0 op_sel_hi:[1,0]
	s_waitcnt vmcnt(5)
	v_pk_fma_f32 v[20:21], v[26:27], v[20:21], v[140:141]
	v_pk_fma_f32 v[22:23], v[24:25], v[22:23], v[142:143]
	v_cvt_pk_bf16_f32 v20, v20, v21
	v_lshl_add_u64 v[78:79], v[62:63], 0, v[50:51]
	v_cvt_pk_bf16_f32 v21, v22, v23
	global_store_dwordx2 v[64:65], v[20:21], off offset:1024
	s_nop 0
	s_waitcnt vmcnt(5)
	v_pk_mul_f32 v[16:17], v[16:17], v[144:145]
	v_pk_mul_f32 v[18:19], v[18:19], v[146:147]
	s_waitcnt vmcnt(4)
	v_pk_add_f32 v[22:23], v[148:149], 1.0 op_sel_hi:[1,0]
	v_pk_add_f32 v[20:21], v[150:151], 1.0 op_sel_hi:[1,0]
	s_waitcnt vmcnt(3)
	v_pk_fma_f32 v[16:17], v[16:17], v[22:23], v[152:153]
	v_pk_fma_f32 v[18:19], v[18:19], v[20:21], v[154:155]
	v_cvt_pk_bf16_f32 v16, v16, v17
	v_lshl_add_u64 v[20:21], v[62:63], 0, v[52:53]
	v_cvt_pk_bf16_f32 v17, v18, v19
	global_store_dwordx2 v[64:65], v[16:17], off offset:1536
	global_load_dwordx4 v[16:19], v[34:35], off
	v_lshl_add_u64 v[24:25], v[60:61], 0, v[52:53]
	global_load_dwordx4 v[20:23], v[20:21], off
	s_waitcnt vmcnt(1)
	v_pk_mul_f32 v[12:13], v[12:13], v[16:17]
	global_load_dwordx4 v[24:27], v[24:25], off
	v_pk_mul_f32 v[14:15], v[14:15], v[18:19]
	s_waitcnt vmcnt(1)
	v_pk_add_f32 v[18:19], v[20:21], 1.0 op_sel_hi:[1,0]
	v_pk_add_f32 v[16:17], v[22:23], 1.0 op_sel_hi:[1,0]
	v_lshl_add_u64 v[20:21], v[60:61], 0, v[54:55]
	s_waitcnt vmcnt(0)
	v_pk_fma_f32 v[12:13], v[12:13], v[18:19], v[24:25]
	v_pk_fma_f32 v[14:15], v[14:15], v[16:17], v[26:27]
	v_cvt_pk_bf16_f32 v12, v12, v13
	v_lshl_add_u64 v[16:17], v[62:63], 0, v[54:55]
	v_cvt_pk_bf16_f32 v13, v14, v15
	global_store_dwordx2 v[64:65], v[12:13], off offset:2048
	global_load_dwordx4 v[12:15], v[36:37], off
	s_waitcnt vmcnt(0)
	v_pk_mul_f32 v[8:9], v[8:9], v[12:13]
	global_load_dwordx4 v[16:19], v[16:17], off
	v_pk_mul_f32 v[10:11], v[10:11], v[14:15]
	global_load_dwordx4 v[20:23], v[20:21], off
	s_waitcnt vmcnt(1)
	v_pk_add_f32 v[14:15], v[16:17], 1.0 op_sel_hi:[1,0]
	v_pk_add_f32 v[12:13], v[18:19], 1.0 op_sel_hi:[1,0]
	s_waitcnt vmcnt(0)
	v_pk_fma_f32 v[8:9], v[8:9], v[14:15], v[20:21]
	v_pk_fma_f32 v[10:11], v[10:11], v[12:13], v[22:23]
	v_cvt_pk_bf16_f32 v8, v8, v9
	v_lshl_add_u64 v[12:13], v[62:63], 0, v[56:57]
	v_cvt_pk_bf16_f32 v9, v10, v11
	global_store_dwordx2 v[64:65], v[8:9], off offset:2560
	global_load_dwordx4 v[8:11], v[38:39], off
	v_lshl_add_u64 v[16:17], v[60:61], 0, v[56:57]
	global_load_dwordx4 v[12:15], v[12:13], off
	s_waitcnt vmcnt(1)
	v_pk_mul_f32 v[4:5], v[4:5], v[8:9]
	global_load_dwordx4 v[16:19], v[16:17], off
	v_pk_mul_f32 v[6:7], v[6:7], v[10:11]
	s_waitcnt vmcnt(1)
	v_pk_add_f32 v[10:11], v[12:13], 1.0 op_sel_hi:[1,0]
	v_pk_add_f32 v[8:9], v[14:15], 1.0 op_sel_hi:[1,0]
	v_lshl_add_u64 v[12:13], v[60:61], 0, v[58:59]
	s_waitcnt vmcnt(0)
	v_pk_fma_f32 v[4:5], v[4:5], v[10:11], v[16:17]
	v_pk_fma_f32 v[6:7], v[6:7], v[8:9], v[18:19]
	v_cvt_pk_bf16_f32 v4, v4, v5
	v_lshl_add_u64 v[8:9], v[62:63], 0, v[58:59]
	v_cvt_pk_bf16_f32 v5, v6, v7
	global_store_dwordx2 v[64:65], v[4:5], off offset:3072
	global_load_dwordx4 v[4:7], v[40:41], off
	s_waitcnt vmcnt(0)
	v_pk_mul_f32 v[0:1], v[0:1], v[4:5]
	global_load_dwordx4 v[8:11], v[8:9], off
	v_pk_mul_f32 v[2:3], v[2:3], v[6:7]
	global_load_dwordx4 v[12:15], v[12:13], off
	s_waitcnt vmcnt(1)
	v_pk_add_f32 v[6:7], v[8:9], 1.0 op_sel_hi:[1,0]
	v_pk_add_f32 v[4:5], v[10:11], 1.0 op_sel_hi:[1,0]
	s_waitcnt vmcnt(0)
	v_pk_fma_f32 v[0:1], v[0:1], v[6:7], v[12:13]
	v_pk_fma_f32 v[2:3], v[2:3], v[4:5], v[14:15]
	v_cvt_pk_bf16_f32 v0, v0, v1
	s_nop 0
	v_cvt_pk_bf16_f32 v1, v2, v3
	global_store_dwordx2 v[64:65], v[0:1], off offset:3584
	s_andn2_b64 exec, exec, s[16:17]
	s_cbranch_execz .LBB0_63
